# P0 pool-weight fold as 16x16 tiles with f32-operand MFMA (each operand read once); P8 conv fix-up phase rewritten by hand (weights once per wave, halo loads batched, next item prefetched)
# speedup vs baseline: 1.0775x; 1.0236x over previous
.LBB0_52:
	s_or_b64 exec, exec, s[0:1]
	v_readlane_b32 s0, v240, 26
	v_readlane_b32 s1, v240, 28
	v_readlane_b32 s10, v240, 14
	v_readlane_b32 s11, v240, 15
	v_readlane_b32 s14, v240, 16
	v_readlane_b32 s15, v240, 17
	v_readlane_b32 s16, v240, 18
	v_readlane_b32 s17, v240, 19
	v_and_b32_e32 v1, 15, v160
	v_lshrrev_b32_e32 v2, 4, v160
	v_lshlrev_b32_e32 v3, 9, v1
	v_lshl_add_u32 v3, v2, 7, v3
	v_lshlrev_b32_e32 v4, 7, v2
	v_lshlrev_b32_e32 v5, 17, v2
	v_lshl_add_u32 v5, v1, 2, v5
	v_lshlrev_b32_e32 v204, 10, v1
	v_lshl_add_u32 v204, v2, 3, v204
.Lwpp_loop:
	s_cmpk_ge_u32 s0, 0x800
	s_cbranch_scc1 .Lwpp_done
	s_lshr_b32 s3, s0, 9
	s_bfe_u32 s5, s0, 0x30006
	s_and_b32 s6, s0, 63
	s_lshl_b32 s7, s3, 7
	s_lshl_b32 s18, s5, 4
	s_add_u32 s18, s18, s7
	s_lshl_b32 s19, s18, 9
	s_add_u32 s28, s10, s19
	s_addc_u32 s29, s11, 0
	s_lshl_b32 s19, s3, 9
	s_add_u32 s30, s14, s19
	s_addc_u32 s31, s15, 0
	s_lshl_b32 s19, s3, 19
	s_lshl_b32 s22, s6, 6
	s_add_u32 s19, s19, s22
	s_add_u32 s34, s16, s19
	s_addc_u32 s35, s17, 0
	s_lshl_b32 s19, s6, 14
	s_lshl_b32 s22, s18, 1
	s_add_u32 s19, s19, s22
	s_add_u32 s19, s19, 0xa80000
	s_add_u32 s36, s94, s19
	s_addc_u32 s37, s95, 0
	global_load_dwordx4 v[8:11], v3, s[28:29]
	global_load_dwordx4 v[12:15], v3, s[28:29] offset:16
	global_load_dwordx4 v[16:19], v3, s[28:29] offset:32
	global_load_dwordx4 v[20:23], v3, s[28:29] offset:48
	global_load_dwordx4 v[24:27], v3, s[28:29] offset:64
	global_load_dwordx4 v[28:31], v3, s[28:29] offset:80
	global_load_dwordx4 v[32:35], v3, s[28:29] offset:96
	global_load_dwordx4 v[36:39], v3, s[28:29] offset:112
	global_load_dwordx4 v[40:43], v4, s[30:31]
	global_load_dwordx4 v[44:47], v4, s[30:31] offset:16
	global_load_dwordx4 v[48:51], v4, s[30:31] offset:32
	global_load_dwordx4 v[52:55], v4, s[30:31] offset:48
	global_load_dwordx4 v[56:59], v4, s[30:31] offset:64
	global_load_dwordx4 v[60:63], v4, s[30:31] offset:80
	global_load_dwordx4 v[64:67], v4, s[30:31] offset:96
	global_load_dwordx4 v[68:71], v4, s[30:31] offset:112
	global_load_dword v72, v5, s[34:35]
	s_add_u32 s34, s34, 0x1000
	s_addc_u32 s35, s35, 0
	global_load_dword v73, v5, s[34:35]
	s_add_u32 s34, s34, 0x1000
	s_addc_u32 s35, s35, 0
	global_load_dword v74, v5, s[34:35]
	s_add_u32 s34, s34, 0x1000
	s_addc_u32 s35, s35, 0
	global_load_dword v75, v5, s[34:35]
	s_add_u32 s34, s34, 0x1000
	s_addc_u32 s35, s35, 0
	global_load_dword v76, v5, s[34:35]
	s_add_u32 s34, s34, 0x1000
	s_addc_u32 s35, s35, 0
	global_load_dword v77, v5, s[34:35]
	s_add_u32 s34, s34, 0x1000
	s_addc_u32 s35, s35, 0
	global_load_dword v78, v5, s[34:35]
	s_add_u32 s34, s34, 0x1000
	s_addc_u32 s35, s35, 0
	global_load_dword v79, v5, s[34:35]
	s_add_u32 s34, s34, 0x1000
	s_addc_u32 s35, s35, 0
	global_load_dword v80, v5, s[34:35]
	s_add_u32 s34, s34, 0x1000
	s_addc_u32 s35, s35, 0
	global_load_dword v81, v5, s[34:35]
	s_add_u32 s34, s34, 0x1000
	s_addc_u32 s35, s35, 0
	global_load_dword v82, v5, s[34:35]
	s_add_u32 s34, s34, 0x1000
	s_addc_u32 s35, s35, 0
	global_load_dword v83, v5, s[34:35]
	s_add_u32 s34, s34, 0x1000
	s_addc_u32 s35, s35, 0
	global_load_dword v84, v5, s[34:35]
	s_add_u32 s34, s34, 0x1000
	s_addc_u32 s35, s35, 0
	global_load_dword v85, v5, s[34:35]
	s_add_u32 s34, s34, 0x1000
	s_addc_u32 s35, s35, 0
	global_load_dword v86, v5, s[34:35]
	s_add_u32 s34, s34, 0x1000
	s_addc_u32 s35, s35, 0
	global_load_dword v87, v5, s[34:35]
	s_add_u32 s34, s34, 0x1000
	s_addc_u32 s35, s35, 0
	global_load_dword v88, v5, s[34:35]
	s_add_u32 s34, s34, 0x1000
	s_addc_u32 s35, s35, 0
	global_load_dword v89, v5, s[34:35]
	s_add_u32 s34, s34, 0x1000
	s_addc_u32 s35, s35, 0
	global_load_dword v90, v5, s[34:35]
	s_add_u32 s34, s34, 0x1000
	s_addc_u32 s35, s35, 0
	global_load_dword v91, v5, s[34:35]
	s_add_u32 s34, s34, 0x1000
	s_addc_u32 s35, s35, 0
	global_load_dword v92, v5, s[34:35]
	s_add_u32 s34, s34, 0x1000
	s_addc_u32 s35, s35, 0
	global_load_dword v93, v5, s[34:35]
	s_add_u32 s34, s34, 0x1000
	s_addc_u32 s35, s35, 0
	global_load_dword v94, v5, s[34:35]
	s_add_u32 s34, s34, 0x1000
	s_addc_u32 s35, s35, 0
	global_load_dword v95, v5, s[34:35]
	s_add_u32 s34, s34, 0x1000
	s_addc_u32 s35, s35, 0
	global_load_dword v96, v5, s[34:35]
	s_add_u32 s34, s34, 0x1000
	s_addc_u32 s35, s35, 0
	global_load_dword v97, v5, s[34:35]
	s_add_u32 s34, s34, 0x1000
	s_addc_u32 s35, s35, 0
	global_load_dword v98, v5, s[34:35]
	s_add_u32 s34, s34, 0x1000
	s_addc_u32 s35, s35, 0
	global_load_dword v99, v5, s[34:35]
	s_add_u32 s34, s34, 0x1000
	s_addc_u32 s35, s35, 0
	global_load_dword v100, v5, s[34:35]
	s_add_u32 s34, s34, 0x1000
	s_addc_u32 s35, s35, 0
	global_load_dword v101, v5, s[34:35]
	s_add_u32 s34, s34, 0x1000
	s_addc_u32 s35, s35, 0
	global_load_dword v102, v5, s[34:35]
	s_add_u32 s34, s34, 0x1000
	s_addc_u32 s35, s35, 0
	global_load_dword v103, v5, s[34:35]
	s_waitcnt vmcnt(32)
	v_mul_f32_e32 v8, v8, v40
	v_mul_f32_e32 v9, v9, v41
	v_mul_f32_e32 v10, v10, v42
	v_mul_f32_e32 v11, v11, v43
	v_mul_f32_e32 v12, v12, v44
	v_mul_f32_e32 v13, v13, v45
	v_mul_f32_e32 v14, v14, v46
	v_mul_f32_e32 v15, v15, v47
	v_mul_f32_e32 v16, v16, v48
	v_mul_f32_e32 v17, v17, v49
	v_mul_f32_e32 v18, v18, v50
	v_mul_f32_e32 v19, v19, v51
	v_mul_f32_e32 v20, v20, v52
	v_mul_f32_e32 v21, v21, v53
	v_mul_f32_e32 v22, v22, v54
	v_mul_f32_e32 v23, v23, v55
	v_mul_f32_e32 v24, v24, v56
	v_mul_f32_e32 v25, v25, v57
	v_mul_f32_e32 v26, v26, v58
	v_mul_f32_e32 v27, v27, v59
	v_mul_f32_e32 v28, v28, v60
	v_mul_f32_e32 v29, v29, v61
	v_mul_f32_e32 v30, v30, v62
	v_mul_f32_e32 v31, v31, v63
	v_mul_f32_e32 v32, v32, v64
	v_mul_f32_e32 v33, v33, v65
	v_mul_f32_e32 v34, v34, v66
	v_mul_f32_e32 v35, v35, v67
	v_mul_f32_e32 v36, v36, v68
	v_mul_f32_e32 v37, v37, v69
	v_mul_f32_e32 v38, v38, v70
	v_mul_f32_e32 v39, v39, v71
	s_waitcnt vmcnt(31)
	v_mfma_f32_16x16x4_f32 v[104:107], v8, v72, 0
	s_waitcnt vmcnt(30)
	v_mfma_f32_16x16x4_f32 v[104:107], v9, v73, v[104:107]
	s_waitcnt vmcnt(29)
	v_mfma_f32_16x16x4_f32 v[104:107], v10, v74, v[104:107]
	s_waitcnt vmcnt(28)
	v_mfma_f32_16x16x4_f32 v[104:107], v11, v75, v[104:107]
	s_waitcnt vmcnt(27)
	v_mfma_f32_16x16x4_f32 v[104:107], v12, v76, v[104:107]
	s_waitcnt vmcnt(26)
	v_mfma_f32_16x16x4_f32 v[104:107], v13, v77, v[104:107]
	s_waitcnt vmcnt(25)
	v_mfma_f32_16x16x4_f32 v[104:107], v14, v78, v[104:107]
	s_waitcnt vmcnt(24)
	v_mfma_f32_16x16x4_f32 v[104:107], v15, v79, v[104:107]
	s_waitcnt vmcnt(23)
	v_mfma_f32_16x16x4_f32 v[104:107], v16, v80, v[104:107]
	s_waitcnt vmcnt(22)
	v_mfma_f32_16x16x4_f32 v[104:107], v17, v81, v[104:107]
	s_waitcnt vmcnt(21)
	v_mfma_f32_16x16x4_f32 v[104:107], v18, v82, v[104:107]
	s_waitcnt vmcnt(20)
	v_mfma_f32_16x16x4_f32 v[104:107], v19, v83, v[104:107]
	s_waitcnt vmcnt(19)
	v_mfma_f32_16x16x4_f32 v[104:107], v20, v84, v[104:107]
	s_waitcnt vmcnt(18)
	v_mfma_f32_16x16x4_f32 v[104:107], v21, v85, v[104:107]
	s_waitcnt vmcnt(17)
	v_mfma_f32_16x16x4_f32 v[104:107], v22, v86, v[104:107]
	s_waitcnt vmcnt(16)
	v_mfma_f32_16x16x4_f32 v[104:107], v23, v87, v[104:107]
	s_waitcnt vmcnt(15)
	v_mfma_f32_16x16x4_f32 v[104:107], v24, v88, v[104:107]
	s_waitcnt vmcnt(14)
	v_mfma_f32_16x16x4_f32 v[104:107], v25, v89, v[104:107]
	s_waitcnt vmcnt(13)
	v_mfma_f32_16x16x4_f32 v[104:107], v26, v90, v[104:107]
	s_waitcnt vmcnt(12)
	v_mfma_f32_16x16x4_f32 v[104:107], v27, v91, v[104:107]
	s_waitcnt vmcnt(11)
	v_mfma_f32_16x16x4_f32 v[104:107], v28, v92, v[104:107]
	s_waitcnt vmcnt(10)
	v_mfma_f32_16x16x4_f32 v[104:107], v29, v93, v[104:107]
	s_waitcnt vmcnt(9)
	v_mfma_f32_16x16x4_f32 v[104:107], v30, v94, v[104:107]
	s_waitcnt vmcnt(8)
	v_mfma_f32_16x16x4_f32 v[104:107], v31, v95, v[104:107]
	s_waitcnt vmcnt(7)
	v_mfma_f32_16x16x4_f32 v[104:107], v32, v96, v[104:107]
	s_waitcnt vmcnt(6)
	v_mfma_f32_16x16x4_f32 v[104:107], v33, v97, v[104:107]
	s_waitcnt vmcnt(5)
	v_mfma_f32_16x16x4_f32 v[104:107], v34, v98, v[104:107]
	s_waitcnt vmcnt(4)
	v_mfma_f32_16x16x4_f32 v[104:107], v35, v99, v[104:107]
	s_waitcnt vmcnt(3)
	v_mfma_f32_16x16x4_f32 v[104:107], v36, v100, v[104:107]
	s_waitcnt vmcnt(2)
	v_mfma_f32_16x16x4_f32 v[104:107], v37, v101, v[104:107]
	s_waitcnt vmcnt(1)
	v_mfma_f32_16x16x4_f32 v[104:107], v38, v102, v[104:107]
	s_waitcnt vmcnt(0)
	v_mfma_f32_16x16x4_f32 v[104:107], v39, v103, v[104:107]
	s_nop 7
	s_nop 3
	v_cvt_pk_bf16_f32 v108, v104, v105
	v_cvt_pk_bf16_f32 v109, v106, v107
	global_store_dwordx2 v204, v[108:109], s[36:37]
	s_add_u32 s0, s0, s1
	s_branch .Lwpp_loop
.Lwpp_done:
.LBB0_57:
	s_mov_b32 s0, 0x10100
	v_cmp_gt_i32_e32 vcc, s0, v6
	s_and_saveexec_b64 s[0:1], vcc
	v_readlane_b32 s36, v240, 30
	v_readlane_b32 s37, v240, 31
	v_readlane_b32 s38, v240, 32
	v_readlane_b32 s39, v240, 33
	v_readlane_b32 s40, v240, 34
	v_readlane_b32 s41, v240, 35
	v_readlane_b32 s42, v240, 36
	v_readlane_b32 s43, v240, 37
	v_readlane_b32 s44, v240, 38
	v_readlane_b32 s45, v240, 39
	v_readlane_b32 s46, v240, 40
	v_readlane_b32 s47, v240, 41
	v_readlane_b32 s48, v240, 42
	v_readlane_b32 s49, v240, 43
	v_readlane_b32 s50, v240, 44
	v_readlane_b32 s51, v240, 45
	s_cbranch_execz .LBB0_70
	s_add_u32 s6, s94, 0x100000
	v_and_b32_e32 v1, 3, v190
	v_readlane_b32 s3, v240, 0
	v_readlane_b32 s5, v240, 25
	s_addc_u32 s7, s95, 0
	v_mov_b32_e32 v2, 0x3fc6c310
	v_mov_b32_e32 v3, 0x3fd43d13
	v_cmp_eq_u32_e32 vcc, 2, v1
	s_lshl_b32 s3, s3, 9
	s_lshl_b32 s5, s5, 6
	v_cndmask_b32_e32 v3, v2, v3, vcc
	v_mov_b32_e32 v2, 0xe3769f3f
	v_mov_b32_e32 v4, 0x6248490f
	s_add_i32 s3, s3, s5
	v_cndmask_b32_e32 v2, v2, v4, vcc
	v_or_b32_e32 v4, s3, v160
	s_waitcnt lgkmcnt(0)
	s_mov_b32 s14, 0x6dc9c883
	v_lshlrev_b32_e32 v4, 1, v4
	s_lshl_b32 s3, s96, 10
	s_mov_b64 s[10:11], 0
	s_mov_b32 s15, 0x3fc45f30
	s_mov_b32 s5, 0x100ff
	v_mov_b32_e32 v8, 0x3c1c381e
	v_mov_b32_e32 v9, 0x3fe1feb3
	v_mov_b32_e32 v7, 0x3f50624d
	v_mov_b32_e32 v16, 0x3f847ae1
	v_mov_b32_e32 v17, 0xd2f1a9fc
	v_mov_b32_e32 v18, 0x47ae147b
	v_mov_b32_e32 v10, 0x9999999a
	v_mov_b32_e32 v11, 0x3fb99999
	s_branch .LBB0_61

.LBB0_1182:
	v_readlane_b32 s4, v240, 2
	v_readlane_b32 s5, v240, 3
	s_cmp_lt_i32 s4, 9
	s_cselect_b64 s[4:5], -1, 0
	s_and_b64 s[0:1], s[4:5], s[0:1]
	s_andn2_b64 vcc, exec, s[0:1]
	s_cbranch_vccnz .LBB0_1198
	v_readlane_b32 s4, v240, 26
	s_cmpk_gt_i32 s4, 0x15ff
	v_readlane_b32 s5, v240, 27
	s_cbranch_scc1 .LBB0_1198
	v_readlane_b32 s4, v240, 26
	v_readlane_b32 s3, v240, 28
	v_readlane_b32 s16, v240, 36
	v_readlane_b32 s17, v240, 37
	v_readlane_b32 s18, v240, 38
	v_readlane_b32 s19, v240, 39
	s_add_u32 s10, s94, 0x1d600000
	s_addc_u32 s11, s95, 0
	s_add_u32 s12, s94, 0x6500000
	s_addc_u32 s13, s95, 0
	s_add_u32 s14, s94, 0x300000
	s_addc_u32 s15, s95, 0
	s_mul_hi_u32 s3, s3, 0x1745d175
	s_mul_hi_u32 s6, s4, 0x1745d175
	s_mul_i32 s5, s6, 11
	s_sub_u32 s7, s4, s5
	s_cmp_ge_u32 s6, s3
	s_cbranch_scc1 .Lp8_done
	s_mov_b32 s36, 0
	s_mov_b32 s37, -1
	s_mov_b32 s40, s6
.Lp8_pass:
	s_add_u32 s20, s40, 0
	s_add_u32 s21, s40, s3
	s_add_u32 s22, s21, s3
	v_lshrrev_b32_e32 v112, 5, v160
	v_and_b32_e32 v113, 31, v160
	s_lshl_b32 s8, s7, 8
	v_lshl_add_u32 v114, v113, 3, s8
	v_lshrrev_b32_e32 v115, 4, v113
	v_and_b32_e32 v116, 15, v113
	s_lshl_b32 s9, s7, 9
	v_lshl_add_u32 v115, v115, 8, s9
	v_lshl_add_u32 v115, v116, 3, v115
	v_mul_u32_u24_e32 v116, 0x1600, v112
	v_add_u32_e32 v116, v116, v115
	v_lshlrev_b32_e32 v130, 1, v116
	v_mul_u32_u24_e32 v116, 0xb00, v112
	v_add_u32_e32 v116, v116, v114
	v_lshlrev_b32_e32 v131, 1, v116
	v_lshlrev_b32_e32 v129, 2, v114
	v_mul_u32_u24_e32 v116, 0x5800, v112
	v_add_u32_e32 v128, v116, v129
	s_mov_b32 s23, -1
	s_and_b32 s5, s20, 63
	s_cmp_eq_u32 s5, 0
	s_cselect_b32 s5, s20, -1
	s_cmpk_lt_u32 s20, 0x200
	s_cselect_b32 s5, s5, -1
	s_cmp_lg_u32 s5, -1
	s_cselect_b32 s23, s5, s23
	s_and_b32 s5, s21, 63
	s_cmp_eq_u32 s5, 0
	s_cselect_b32 s5, s21, -1
	s_cmpk_lt_u32 s21, 0x200
	s_cselect_b32 s5, s5, -1
	s_cmp_lg_u32 s5, -1
	s_cselect_b32 s23, s5, s23
	s_and_b32 s5, s22, 63
	s_cmp_eq_u32 s5, 0
	s_cselect_b32 s5, s22, -1
	s_cmpk_lt_u32 s22, 0x200
	s_cselect_b32 s5, s5, -1
	s_cmp_lg_u32 s5, -1
	s_cselect_b32 s23, s5, s23
	s_cmp_eq_u32 s23, -1
	s_cbranch_scc1 .Lp8_wload
	s_min_u32 s5, s23, 0x1ff
	s_mul_i32 s5, s5, 0xb000
	s_add_u32 s24, s10, s5
	s_addc_u32 s25, s11, 0
	s_sub_u32 s26, s24, 0x2c00
	s_subb_u32 s27, s25, 0
	s_sub_u32 s28, s24, 0x5800
	s_subb_u32 s29, s25, 0
	global_load_dwordx4 v[64:67], v130, s[24:25]
	global_load_dwordx4 v[68:71], v130, s[24:25] offset:256
	global_load_dwordx4 v[72:75], v130, s[26:27]
	global_load_dwordx4 v[76:79], v130, s[26:27] offset:256
	s_add_u32 s34, s14, 0
	s_addc_u32 s35, s15, 0
	s_add_u32 s38, s14, 0x2c00
	s_addc_u32 s39, s15, 0
	v_mov_b32_e32 v80, 0
	v_mov_b32_e32 v81, 0
	v_mov_b32_e32 v82, 0
	v_mov_b32_e32 v83, 0
	v_mov_b32_e32 v84, 0
	v_mov_b32_e32 v85, 0
	v_mov_b32_e32 v86, 0
	v_mov_b32_e32 v87, 0
	v_mov_b32_e32 v88, 0
	v_mov_b32_e32 v89, 0
	v_mov_b32_e32 v90, 0
	v_mov_b32_e32 v91, 0
	v_mov_b32_e32 v92, 0
	v_mov_b32_e32 v93, 0
	v_mov_b32_e32 v94, 0
	v_mov_b32_e32 v95, 0
	global_load_dwordx4 v[0:3], v128, s[34:35]
	global_load_dwordx4 v[4:7], v128, s[34:35] offset:16
	global_load_dwordx4 v[8:11], v128, s[38:39]
	global_load_dwordx4 v[12:15], v128, s[38:39] offset:16
	s_add_u32 s34, s34, 0xb000
	s_addc_u32 s35, s35, 0
	s_add_u32 s38, s38, 0xb000
	s_addc_u32 s39, s39, 0
	global_load_dwordx4 v[16:19], v128, s[34:35]
	global_load_dwordx4 v[20:23], v128, s[34:35] offset:16
	global_load_dwordx4 v[24:27], v128, s[38:39]
	global_load_dwordx4 v[28:31], v128, s[38:39] offset:16
	s_add_u32 s34, s34, 0xb000
	s_addc_u32 s35, s35, 0
	s_add_u32 s38, s38, 0xb000
	s_addc_u32 s39, s39, 0
	global_load_dwordx4 v[32:35], v128, s[34:35]
	global_load_dwordx4 v[36:39], v128, s[34:35] offset:16
	global_load_dwordx4 v[40:43], v128, s[38:39]
	global_load_dwordx4 v[44:47], v128, s[38:39] offset:16
	s_add_u32 s34, s34, 0xb000
	s_addc_u32 s35, s35, 0
	s_add_u32 s38, s38, 0xb000
	s_addc_u32 s39, s39, 0
	global_load_dwordx4 v[48:51], v128, s[34:35]
	global_load_dwordx4 v[52:55], v128, s[34:35] offset:16
	global_load_dwordx4 v[56:59], v128, s[38:39]
	global_load_dwordx4 v[60:63], v128, s[38:39] offset:16
	s_add_u32 s34, s34, 0xb000
	s_addc_u32 s35, s35, 0
	s_add_u32 s38, s38, 0xb000
	s_addc_u32 s39, s39, 0
	s_waitcnt vmcnt(12)
	v_add_f32_e32 v80, v80, v0
	v_add_f32_e32 v81, v81, v1
	v_add_f32_e32 v82, v82, v2
	v_add_f32_e32 v83, v83, v3
	v_add_f32_e32 v84, v84, v4
	v_add_f32_e32 v85, v85, v5
	v_add_f32_e32 v86, v86, v6
	v_add_f32_e32 v87, v87, v7
	v_add_f32_e32 v88, v88, v8
	v_add_f32_e32 v89, v89, v9
	v_add_f32_e32 v90, v90, v10
	v_add_f32_e32 v91, v91, v11
	v_add_f32_e32 v92, v92, v12
	v_add_f32_e32 v93, v93, v13
	v_add_f32_e32 v94, v94, v14
	v_add_f32_e32 v95, v95, v15
	global_load_dwordx4 v[0:3], v128, s[34:35]
	global_load_dwordx4 v[4:7], v128, s[34:35] offset:16
	global_load_dwordx4 v[8:11], v128, s[38:39]
	global_load_dwordx4 v[12:15], v128, s[38:39] offset:16
	s_add_u32 s34, s34, 0xb000
	s_addc_u32 s35, s35, 0
	s_add_u32 s38, s38, 0xb000
	s_addc_u32 s39, s39, 0
	s_waitcnt vmcnt(12)
	v_add_f32_e32 v80, v80, v16
	v_add_f32_e32 v81, v81, v17
	v_add_f32_e32 v82, v82, v18
	v_add_f32_e32 v83, v83, v19
	v_add_f32_e32 v84, v84, v20
	v_add_f32_e32 v85, v85, v21
	v_add_f32_e32 v86, v86, v22
	v_add_f32_e32 v87, v87, v23
	v_add_f32_e32 v88, v88, v24
	v_add_f32_e32 v89, v89, v25
	v_add_f32_e32 v90, v90, v26
	v_add_f32_e32 v91, v91, v27
	v_add_f32_e32 v92, v92, v28
	v_add_f32_e32 v93, v93, v29
	v_add_f32_e32 v94, v94, v30
	v_add_f32_e32 v95, v95, v31
	global_load_dwordx4 v[16:19], v128, s[34:35]
	global_load_dwordx4 v[20:23], v128, s[34:35] offset:16
	global_load_dwordx4 v[24:27], v128, s[38:39]
	global_load_dwordx4 v[28:31], v128, s[38:39] offset:16
	s_add_u32 s34, s34, 0xb000
	s_addc_u32 s35, s35, 0
	s_add_u32 s38, s38, 0xb000
	s_addc_u32 s39, s39, 0
	s_waitcnt vmcnt(12)
	v_add_f32_e32 v80, v80, v32
	v_add_f32_e32 v81, v81, v33
	v_add_f32_e32 v82, v82, v34
	v_add_f32_e32 v83, v83, v35
	v_add_f32_e32 v84, v84, v36
	v_add_f32_e32 v85, v85, v37
	v_add_f32_e32 v86, v86, v38
	v_add_f32_e32 v87, v87, v39
	v_add_f32_e32 v88, v88, v40
	v_add_f32_e32 v89, v89, v41
	v_add_f32_e32 v90, v90, v42
	v_add_f32_e32 v91, v91, v43
	v_add_f32_e32 v92, v92, v44
	v_add_f32_e32 v93, v93, v45
	v_add_f32_e32 v94, v94, v46
	v_add_f32_e32 v95, v95, v47
	global_load_dwordx4 v[32:35], v128, s[34:35]
	global_load_dwordx4 v[36:39], v128, s[34:35] offset:16
	global_load_dwordx4 v[40:43], v128, s[38:39]
	global_load_dwordx4 v[44:47], v128, s[38:39] offset:16
	s_add_u32 s34, s34, 0xb000
	s_addc_u32 s35, s35, 0
	s_add_u32 s38, s38, 0xb000
	s_addc_u32 s39, s39, 0
	s_waitcnt vmcnt(12)
	v_add_f32_e32 v80, v80, v48
	v_add_f32_e32 v81, v81, v49
	v_add_f32_e32 v82, v82, v50
	v_add_f32_e32 v83, v83, v51
	v_add_f32_e32 v84, v84, v52
	v_add_f32_e32 v85, v85, v53
	v_add_f32_e32 v86, v86, v54
	v_add_f32_e32 v87, v87, v55
	v_add_f32_e32 v88, v88, v56
	v_add_f32_e32 v89, v89, v57
	v_add_f32_e32 v90, v90, v58
	v_add_f32_e32 v91, v91, v59
	v_add_f32_e32 v92, v92, v60
	v_add_f32_e32 v93, v93, v61
	v_add_f32_e32 v94, v94, v62
	v_add_f32_e32 v95, v95, v63
	global_load_dwordx4 v[48:51], v128, s[34:35]
	global_load_dwordx4 v[52:55], v128, s[34:35] offset:16
	global_load_dwordx4 v[56:59], v128, s[38:39]
	global_load_dwordx4 v[60:63], v128, s[38:39] offset:16
	s_add_u32 s34, s34, 0xb000
	s_addc_u32 s35, s35, 0
	s_add_u32 s38, s38, 0xb000
	s_addc_u32 s39, s39, 0
	s_waitcnt vmcnt(12)
	v_add_f32_e32 v80, v80, v0
	v_add_f32_e32 v81, v81, v1
	v_add_f32_e32 v82, v82, v2
	v_add_f32_e32 v83, v83, v3
	v_add_f32_e32 v84, v84, v4
	v_add_f32_e32 v85, v85, v5
	v_add_f32_e32 v86, v86, v6
	v_add_f32_e32 v87, v87, v7
	v_add_f32_e32 v88, v88, v8
	v_add_f32_e32 v89, v89, v9
	v_add_f32_e32 v90, v90, v10
	v_add_f32_e32 v91, v91, v11
	v_add_f32_e32 v92, v92, v12
	v_add_f32_e32 v93, v93, v13
	v_add_f32_e32 v94, v94, v14
	v_add_f32_e32 v95, v95, v15
	global_load_dwordx4 v[0:3], v128, s[34:35]
	global_load_dwordx4 v[4:7], v128, s[34:35] offset:16
	global_load_dwordx4 v[8:11], v128, s[38:39]
	global_load_dwordx4 v[12:15], v128, s[38:39] offset:16
	s_add_u32 s34, s34, 0xb000
	s_addc_u32 s35, s35, 0
	s_add_u32 s38, s38, 0xb000
	s_addc_u32 s39, s39, 0
	s_waitcnt vmcnt(12)
	v_add_f32_e32 v80, v80, v16
	v_add_f32_e32 v81, v81, v17
	v_add_f32_e32 v82, v82, v18
	v_add_f32_e32 v83, v83, v19
	v_add_f32_e32 v84, v84, v20
	v_add_f32_e32 v85, v85, v21
	v_add_f32_e32 v86, v86, v22
	v_add_f32_e32 v87, v87, v23
	v_add_f32_e32 v88, v88, v24
	v_add_f32_e32 v89, v89, v25
	v_add_f32_e32 v90, v90, v26
	v_add_f32_e32 v91, v91, v27
	v_add_f32_e32 v92, v92, v28
	v_add_f32_e32 v93, v93, v29
	v_add_f32_e32 v94, v94, v30
	v_add_f32_e32 v95, v95, v31
	global_load_dwordx4 v[16:19], v128, s[34:35]
	global_load_dwordx4 v[20:23], v128, s[34:35] offset:16
	global_load_dwordx4 v[24:27], v128, s[38:39]
	global_load_dwordx4 v[28:31], v128, s[38:39] offset:16
	s_add_u32 s34, s34, 0xb000
	s_addc_u32 s35, s35, 0
	s_add_u32 s38, s38, 0xb000
	s_addc_u32 s39, s39, 0
	s_waitcnt vmcnt(12)
	v_add_f32_e32 v80, v80, v32
	v_add_f32_e32 v81, v81, v33
	v_add_f32_e32 v82, v82, v34
	v_add_f32_e32 v83, v83, v35
	v_add_f32_e32 v84, v84, v36
	v_add_f32_e32 v85, v85, v37
	v_add_f32_e32 v86, v86, v38
	v_add_f32_e32 v87, v87, v39
	v_add_f32_e32 v88, v88, v40
	v_add_f32_e32 v89, v89, v41
	v_add_f32_e32 v90, v90, v42
	v_add_f32_e32 v91, v91, v43
	v_add_f32_e32 v92, v92, v44
	v_add_f32_e32 v93, v93, v45
	v_add_f32_e32 v94, v94, v46
	v_add_f32_e32 v95, v95, v47
	global_load_dwordx4 v[32:35], v128, s[34:35]
	global_load_dwordx4 v[36:39], v128, s[34:35] offset:16
	global_load_dwordx4 v[40:43], v128, s[38:39]
	global_load_dwordx4 v[44:47], v128, s[38:39] offset:16
	s_add_u32 s34, s34, 0xb000
	s_addc_u32 s35, s35, 0
	s_add_u32 s38, s38, 0xb000
	s_addc_u32 s39, s39, 0
	s_waitcnt vmcnt(12)
	v_add_f32_e32 v80, v80, v48
	v_add_f32_e32 v81, v81, v49
	v_add_f32_e32 v82, v82, v50
	v_add_f32_e32 v83, v83, v51
	v_add_f32_e32 v84, v84, v52
	v_add_f32_e32 v85, v85, v53
	v_add_f32_e32 v86, v86, v54
	v_add_f32_e32 v87, v87, v55
	v_add_f32_e32 v88, v88, v56
	v_add_f32_e32 v89, v89, v57
	v_add_f32_e32 v90, v90, v58
	v_add_f32_e32 v91, v91, v59
	v_add_f32_e32 v92, v92, v60
	v_add_f32_e32 v93, v93, v61
	v_add_f32_e32 v94, v94, v62
	v_add_f32_e32 v95, v95, v63
	global_load_dwordx4 v[48:51], v128, s[34:35]
	global_load_dwordx4 v[52:55], v128, s[34:35] offset:16
	global_load_dwordx4 v[56:59], v128, s[38:39]
	global_load_dwordx4 v[60:63], v128, s[38:39] offset:16
	s_add_u32 s34, s34, 0xb000
	s_addc_u32 s35, s35, 0
	s_add_u32 s38, s38, 0xb000
	s_addc_u32 s39, s39, 0
	s_waitcnt vmcnt(12)
	v_add_f32_e32 v80, v80, v0
	v_add_f32_e32 v81, v81, v1
	v_add_f32_e32 v82, v82, v2
	v_add_f32_e32 v83, v83, v3
	v_add_f32_e32 v84, v84, v4
	v_add_f32_e32 v85, v85, v5
	v_add_f32_e32 v86, v86, v6
	v_add_f32_e32 v87, v87, v7
	v_add_f32_e32 v88, v88, v8
	v_add_f32_e32 v89, v89, v9
	v_add_f32_e32 v90, v90, v10
	v_add_f32_e32 v91, v91, v11
	v_add_f32_e32 v92, v92, v12
	v_add_f32_e32 v93, v93, v13
	v_add_f32_e32 v94, v94, v14
	v_add_f32_e32 v95, v95, v15
	global_load_dwordx4 v[0:3], v128, s[34:35]
	global_load_dwordx4 v[4:7], v128, s[34:35] offset:16
	global_load_dwordx4 v[8:11], v128, s[38:39]
	global_load_dwordx4 v[12:15], v128, s[38:39] offset:16
	s_add_u32 s34, s34, 0xb000
	s_addc_u32 s35, s35, 0
	s_add_u32 s38, s38, 0xb000
	s_addc_u32 s39, s39, 0
	s_waitcnt vmcnt(12)
	v_add_f32_e32 v80, v80, v16
	v_add_f32_e32 v81, v81, v17
	v_add_f32_e32 v82, v82, v18
	v_add_f32_e32 v83, v83, v19
	v_add_f32_e32 v84, v84, v20
	v_add_f32_e32 v85, v85, v21
	v_add_f32_e32 v86, v86, v22
	v_add_f32_e32 v87, v87, v23
	v_add_f32_e32 v88, v88, v24
	v_add_f32_e32 v89, v89, v25
	v_add_f32_e32 v90, v90, v26
	v_add_f32_e32 v91, v91, v27
	v_add_f32_e32 v92, v92, v28
	v_add_f32_e32 v93, v93, v29
	v_add_f32_e32 v94, v94, v30
	v_add_f32_e32 v95, v95, v31
	global_load_dwordx4 v[16:19], v128, s[34:35]
	global_load_dwordx4 v[20:23], v128, s[34:35] offset:16
	global_load_dwordx4 v[24:27], v128, s[38:39]
	global_load_dwordx4 v[28:31], v128, s[38:39] offset:16
	s_add_u32 s34, s34, 0xb000
	s_addc_u32 s35, s35, 0
	s_add_u32 s38, s38, 0xb000
	s_addc_u32 s39, s39, 0
	s_waitcnt vmcnt(12)
	v_add_f32_e32 v80, v80, v32
	v_add_f32_e32 v81, v81, v33
	v_add_f32_e32 v82, v82, v34
	v_add_f32_e32 v83, v83, v35
	v_add_f32_e32 v84, v84, v36
	v_add_f32_e32 v85, v85, v37
	v_add_f32_e32 v86, v86, v38
	v_add_f32_e32 v87, v87, v39
	v_add_f32_e32 v88, v88, v40
	v_add_f32_e32 v89, v89, v41
	v_add_f32_e32 v90, v90, v42
	v_add_f32_e32 v91, v91, v43
	v_add_f32_e32 v92, v92, v44
	v_add_f32_e32 v93, v93, v45
	v_add_f32_e32 v94, v94, v46
	v_add_f32_e32 v95, v95, v47
	global_load_dwordx4 v[32:35], v128, s[34:35]
	global_load_dwordx4 v[36:39], v128, s[34:35] offset:16
	global_load_dwordx4 v[40:43], v128, s[38:39]
	global_load_dwordx4 v[44:47], v128, s[38:39] offset:16
	s_add_u32 s34, s34, 0xb000
	s_addc_u32 s35, s35, 0
	s_add_u32 s38, s38, 0xb000
	s_addc_u32 s39, s39, 0
	s_waitcnt vmcnt(12)
	v_add_f32_e32 v80, v80, v48
	v_add_f32_e32 v81, v81, v49
	v_add_f32_e32 v82, v82, v50
	v_add_f32_e32 v83, v83, v51
	v_add_f32_e32 v84, v84, v52
	v_add_f32_e32 v85, v85, v53
	v_add_f32_e32 v86, v86, v54
	v_add_f32_e32 v87, v87, v55
	v_add_f32_e32 v88, v88, v56
	v_add_f32_e32 v89, v89, v57
	v_add_f32_e32 v90, v90, v58
	v_add_f32_e32 v91, v91, v59
	v_add_f32_e32 v92, v92, v60
	v_add_f32_e32 v93, v93, v61
	v_add_f32_e32 v94, v94, v62
	v_add_f32_e32 v95, v95, v63
	global_load_dwordx4 v[48:51], v128, s[34:35]
	global_load_dwordx4 v[52:55], v128, s[34:35] offset:16
	global_load_dwordx4 v[56:59], v128, s[38:39]
	global_load_dwordx4 v[60:63], v128, s[38:39] offset:16
	s_waitcnt vmcnt(12)
	v_add_f32_e32 v80, v80, v0
	v_add_f32_e32 v81, v81, v1
	v_add_f32_e32 v82, v82, v2
	v_add_f32_e32 v83, v83, v3
	v_add_f32_e32 v84, v84, v4
	v_add_f32_e32 v85, v85, v5
	v_add_f32_e32 v86, v86, v6
	v_add_f32_e32 v87, v87, v7
	v_add_f32_e32 v88, v88, v8
	v_add_f32_e32 v89, v89, v9
	v_add_f32_e32 v90, v90, v10
	v_add_f32_e32 v91, v91, v11
	v_add_f32_e32 v92, v92, v12
	v_add_f32_e32 v93, v93, v13
	v_add_f32_e32 v94, v94, v14
	v_add_f32_e32 v95, v95, v15
	s_waitcnt vmcnt(8)
	v_add_f32_e32 v80, v80, v16
	v_add_f32_e32 v81, v81, v17
	v_add_f32_e32 v82, v82, v18
	v_add_f32_e32 v83, v83, v19
	v_add_f32_e32 v84, v84, v20
	v_add_f32_e32 v85, v85, v21
	v_add_f32_e32 v86, v86, v22
	v_add_f32_e32 v87, v87, v23
	v_add_f32_e32 v88, v88, v24
	v_add_f32_e32 v89, v89, v25
	v_add_f32_e32 v90, v90, v26
	v_add_f32_e32 v91, v91, v27
	v_add_f32_e32 v92, v92, v28
	v_add_f32_e32 v93, v93, v29
	v_add_f32_e32 v94, v94, v30
	v_add_f32_e32 v95, v95, v31
	s_waitcnt vmcnt(4)
	v_add_f32_e32 v80, v80, v32
	v_add_f32_e32 v81, v81, v33
	v_add_f32_e32 v82, v82, v34
	v_add_f32_e32 v83, v83, v35
	v_add_f32_e32 v84, v84, v36
	v_add_f32_e32 v85, v85, v37
	v_add_f32_e32 v86, v86, v38
	v_add_f32_e32 v87, v87, v39
	v_add_f32_e32 v88, v88, v40
	v_add_f32_e32 v89, v89, v41
	v_add_f32_e32 v90, v90, v42
	v_add_f32_e32 v91, v91, v43
	v_add_f32_e32 v92, v92, v44
	v_add_f32_e32 v93, v93, v45
	v_add_f32_e32 v94, v94, v46
	v_add_f32_e32 v95, v95, v47
	s_waitcnt vmcnt(0)
	v_add_f32_e32 v80, v80, v48
	v_add_f32_e32 v81, v81, v49
	v_add_f32_e32 v82, v82, v50
	v_add_f32_e32 v83, v83, v51
	v_add_f32_e32 v84, v84, v52
	v_add_f32_e32 v85, v85, v53
	v_add_f32_e32 v86, v86, v54
	v_add_f32_e32 v87, v87, v55
	v_add_f32_e32 v88, v88, v56
	v_add_f32_e32 v89, v89, v57
	v_add_f32_e32 v90, v90, v58
	v_add_f32_e32 v91, v91, v59
	v_add_f32_e32 v92, v92, v60
	v_add_f32_e32 v93, v93, v61
	v_add_f32_e32 v94, v94, v62
	v_add_f32_e32 v95, v95, v63
.Lp8_wload:
	s_add_u32 s34, s16, 0
	s_addc_u32 s35, s17, 0
	global_load_dwordx4 v[0:3], v129, s[34:35]
	global_load_dwordx4 v[4:7], v129, s[34:35] offset:16
	s_add_u32 s34, s16, 0x2c00
	s_addc_u32 s35, s17, 0
	global_load_dwordx4 v[8:11], v129, s[34:35]
	global_load_dwordx4 v[12:15], v129, s[34:35] offset:16
	s_add_u32 s34, s16, 0x5800
	s_addc_u32 s35, s17, 0
	global_load_dwordx4 v[16:19], v129, s[34:35]
	global_load_dwordx4 v[20:23], v129, s[34:35] offset:16
	s_add_u32 s34, s16, 0x8400
	s_addc_u32 s35, s17, 0
	global_load_dwordx4 v[24:27], v129, s[34:35]
	global_load_dwordx4 v[28:31], v129, s[34:35] offset:16
	s_add_u32 s34, s16, 0xb000
	s_addc_u32 s35, s17, 0
	global_load_dwordx4 v[32:35], v129, s[34:35]
	global_load_dwordx4 v[36:39], v129, s[34:35] offset:16
	s_add_u32 s34, s16, 0xdc00
	s_addc_u32 s35, s17, 0
	global_load_dwordx4 v[40:43], v129, s[34:35]
	global_load_dwordx4 v[44:47], v129, s[34:35] offset:16
	s_add_u32 s34, s18, 0
	s_addc_u32 s35, s19, 0
	global_load_dwordx4 v[48:51], v129, s[34:35]
	global_load_dwordx4 v[52:55], v129, s[34:35] offset:16
	s_add_u32 s34, s18, 0x2c00
	s_addc_u32 s35, s19, 0
	global_load_dwordx4 v[56:59], v129, s[34:35]
	global_load_dwordx4 v[60:63], v129, s[34:35] offset:16
	s_cmp_eq_u32 s23, -1
	s_cbranch_scc1 .Lp8_main
	s_waitcnt vmcnt(0)
	s_mul_i32 s5, s23, 0x58000
	s_add_u32 s30, s12, s5
	s_addc_u32 s31, s13, 0
	v_lshlrev_b32_e32 v114, 16, v64
	v_lshlrev_b32_e32 v115, 16, v72
	v_mov_b32_e32 v112, v80
	v_mov_b32_e32 v113, v80
	s_nop 1
	v_permlane32_swap_b32_e32 v112, v113
	v_cndmask_b32_e64 v116, v113, v115, s[36:37]
	v_fma_f32 v96, v0, v80, v48
	v_fmac_f32_e32 v96, v16, v116
	v_fmac_f32_e32 v96, v32, v114
	v_and_b32_e32 v114, 0xffff0000, v64
	v_and_b32_e32 v115, 0xffff0000, v72
	v_mov_b32_e32 v112, v81
	v_mov_b32_e32 v113, v81
	s_nop 1
	v_permlane32_swap_b32_e32 v112, v113
	v_cndmask_b32_e64 v116, v113, v115, s[36:37]
	v_fma_f32 v97, v1, v81, v49
	v_fmac_f32_e32 v97, v17, v116
	v_fmac_f32_e32 v97, v33, v114
	v_lshlrev_b32_e32 v114, 16, v65
	v_lshlrev_b32_e32 v115, 16, v73
	v_mov_b32_e32 v112, v82
	v_mov_b32_e32 v113, v82
	s_nop 1
	v_permlane32_swap_b32_e32 v112, v113
	v_cndmask_b32_e64 v116, v113, v115, s[36:37]
	v_fma_f32 v98, v2, v82, v50
	v_fmac_f32_e32 v98, v18, v116
	v_fmac_f32_e32 v98, v34, v114
	v_and_b32_e32 v114, 0xffff0000, v65
	v_and_b32_e32 v115, 0xffff0000, v73
	v_mov_b32_e32 v112, v83
	v_mov_b32_e32 v113, v83
	s_nop 1
	v_permlane32_swap_b32_e32 v112, v113
	v_cndmask_b32_e64 v116, v113, v115, s[36:37]
	v_fma_f32 v99, v3, v83, v51
	v_fmac_f32_e32 v99, v19, v116
	v_fmac_f32_e32 v99, v35, v114
	v_lshlrev_b32_e32 v114, 16, v66
	v_lshlrev_b32_e32 v115, 16, v74
	v_mov_b32_e32 v112, v84
	v_mov_b32_e32 v113, v84
	s_nop 1
	v_permlane32_swap_b32_e32 v112, v113
	v_cndmask_b32_e64 v116, v113, v115, s[36:37]
	v_fma_f32 v100, v4, v84, v52
	v_fmac_f32_e32 v100, v20, v116
	v_fmac_f32_e32 v100, v36, v114
	v_and_b32_e32 v114, 0xffff0000, v66
	v_and_b32_e32 v115, 0xffff0000, v74
	v_mov_b32_e32 v112, v85
	v_mov_b32_e32 v113, v85
	s_nop 1
	v_permlane32_swap_b32_e32 v112, v113
	v_cndmask_b32_e64 v116, v113, v115, s[36:37]
	v_fma_f32 v101, v5, v85, v53
	v_fmac_f32_e32 v101, v21, v116
	v_fmac_f32_e32 v101, v37, v114
	v_lshlrev_b32_e32 v114, 16, v67
	v_lshlrev_b32_e32 v115, 16, v75
	v_mov_b32_e32 v112, v86
	v_mov_b32_e32 v113, v86
	s_nop 1
	v_permlane32_swap_b32_e32 v112, v113
	v_cndmask_b32_e64 v116, v113, v115, s[36:37]
	v_fma_f32 v102, v6, v86, v54
	v_fmac_f32_e32 v102, v22, v116
	v_fmac_f32_e32 v102, v38, v114
	v_and_b32_e32 v114, 0xffff0000, v67
	v_and_b32_e32 v115, 0xffff0000, v75
	v_mov_b32_e32 v112, v87
	v_mov_b32_e32 v113, v87
	s_nop 1
	v_permlane32_swap_b32_e32 v112, v113
	v_cndmask_b32_e64 v116, v113, v115, s[36:37]
	v_fma_f32 v103, v7, v87, v55
	v_fmac_f32_e32 v103, v23, v116
	v_fmac_f32_e32 v103, v39, v114
	v_lshlrev_b32_e32 v114, 16, v68
	v_lshlrev_b32_e32 v115, 16, v76
	v_mov_b32_e32 v112, v88
	v_mov_b32_e32 v113, v88
	s_nop 1
	v_permlane32_swap_b32_e32 v112, v113
	v_cndmask_b32_e64 v116, v113, v115, s[36:37]
	v_fma_f32 v104, v8, v88, v56
	v_fmac_f32_e32 v104, v24, v116
	v_fmac_f32_e32 v104, v40, v114
	v_and_b32_e32 v114, 0xffff0000, v68
	v_and_b32_e32 v115, 0xffff0000, v76
	v_mov_b32_e32 v112, v89
	v_mov_b32_e32 v113, v89
	s_nop 1
	v_permlane32_swap_b32_e32 v112, v113
	v_cndmask_b32_e64 v116, v113, v115, s[36:37]
	v_fma_f32 v105, v9, v89, v57
	v_fmac_f32_e32 v105, v25, v116
	v_fmac_f32_e32 v105, v41, v114
	v_lshlrev_b32_e32 v114, 16, v69
	v_lshlrev_b32_e32 v115, 16, v77
	v_mov_b32_e32 v112, v90
	v_mov_b32_e32 v113, v90
	s_nop 1
	v_permlane32_swap_b32_e32 v112, v113
	v_cndmask_b32_e64 v116, v113, v115, s[36:37]
	v_fma_f32 v106, v10, v90, v58
	v_fmac_f32_e32 v106, v26, v116
	v_fmac_f32_e32 v106, v42, v114
	v_and_b32_e32 v114, 0xffff0000, v69
	v_and_b32_e32 v115, 0xffff0000, v77
	v_mov_b32_e32 v112, v91
	v_mov_b32_e32 v113, v91
	s_nop 1
	v_permlane32_swap_b32_e32 v112, v113
	v_cndmask_b32_e64 v116, v113, v115, s[36:37]
	v_fma_f32 v107, v11, v91, v59
	v_fmac_f32_e32 v107, v27, v116
	v_fmac_f32_e32 v107, v43, v114
	v_lshlrev_b32_e32 v114, 16, v70
	v_lshlrev_b32_e32 v115, 16, v78
	v_mov_b32_e32 v112, v92
	v_mov_b32_e32 v113, v92
	s_nop 1
	v_permlane32_swap_b32_e32 v112, v113
	v_cndmask_b32_e64 v116, v113, v115, s[36:37]
	v_fma_f32 v108, v12, v92, v60
	v_fmac_f32_e32 v108, v28, v116
	v_fmac_f32_e32 v108, v44, v114
	v_and_b32_e32 v114, 0xffff0000, v70
	v_and_b32_e32 v115, 0xffff0000, v78
	v_mov_b32_e32 v112, v93
	v_mov_b32_e32 v113, v93
	s_nop 1
	v_permlane32_swap_b32_e32 v112, v113
	v_cndmask_b32_e64 v116, v113, v115, s[36:37]
	v_fma_f32 v109, v13, v93, v61
	v_fmac_f32_e32 v109, v29, v116
	v_fmac_f32_e32 v109, v45, v114
	v_lshlrev_b32_e32 v114, 16, v71
	v_lshlrev_b32_e32 v115, 16, v79
	v_mov_b32_e32 v112, v94
	v_mov_b32_e32 v113, v94
	s_nop 1
	v_permlane32_swap_b32_e32 v112, v113
	v_cndmask_b32_e64 v116, v113, v115, s[36:37]
	v_fma_f32 v110, v14, v94, v62
	v_fmac_f32_e32 v110, v30, v116
	v_fmac_f32_e32 v110, v46, v114
	v_and_b32_e32 v114, 0xffff0000, v71
	v_and_b32_e32 v115, 0xffff0000, v79
	v_mov_b32_e32 v112, v95
	v_mov_b32_e32 v113, v95
	s_nop 1
	v_permlane32_swap_b32_e32 v112, v113
	v_cndmask_b32_e64 v116, v113, v115, s[36:37]
	v_fma_f32 v111, v15, v95, v63
	v_fmac_f32_e32 v111, v31, v116
	v_fmac_f32_e32 v111, v47, v114
	v_mul_f32_e32 v118, 0xbfb8aa3b, v96
	v_mul_f32_e32 v119, 0xbfb8aa3b, v97
	v_mul_f32_e32 v120, 0xbfb8aa3b, v98
	v_mul_f32_e32 v121, 0xbfb8aa3b, v99
	v_mul_f32_e32 v122, 0xbfb8aa3b, v100
	v_mul_f32_e32 v123, 0xbfb8aa3b, v101
	v_mul_f32_e32 v124, 0xbfb8aa3b, v102
	v_mul_f32_e32 v125, 0xbfb8aa3b, v103
	v_exp_f32_e32 v118, v118
	v_exp_f32_e32 v119, v119
	v_exp_f32_e32 v120, v120
	v_exp_f32_e32 v121, v121
	v_exp_f32_e32 v122, v122
	v_exp_f32_e32 v123, v123
	v_exp_f32_e32 v124, v124
	v_exp_f32_e32 v125, v125
	v_add_f32_e32 v118, 1.0, v118
	v_add_f32_e32 v119, 1.0, v119
	v_add_f32_e32 v120, 1.0, v120
	v_add_f32_e32 v121, 1.0, v121
	v_add_f32_e32 v122, 1.0, v122
	v_add_f32_e32 v123, 1.0, v123
	v_add_f32_e32 v124, 1.0, v124
	v_add_f32_e32 v125, 1.0, v125
	v_rcp_f32_e32 v118, v118
	v_rcp_f32_e32 v119, v119
	v_rcp_f32_e32 v120, v120
	v_rcp_f32_e32 v121, v121
	v_rcp_f32_e32 v122, v122
	v_rcp_f32_e32 v123, v123
	v_rcp_f32_e32 v124, v124
	v_rcp_f32_e32 v125, v125
	v_mul_f32_e32 v118, v96, v118
	v_mul_f32_e32 v119, v97, v119
	v_mul_f32_e32 v120, v98, v120
	v_mul_f32_e32 v121, v99, v121
	v_mul_f32_e32 v122, v100, v122
	v_mul_f32_e32 v123, v101, v123
	v_mul_f32_e32 v124, v102, v124
	v_mul_f32_e32 v125, v103, v125
	v_mul_f32_e32 v118, v118, v104
	v_mul_f32_e32 v119, v119, v105
	v_mul_f32_e32 v120, v120, v106
	v_mul_f32_e32 v121, v121, v107
	v_mul_f32_e32 v122, v122, v108
	v_mul_f32_e32 v123, v123, v109
	v_mul_f32_e32 v124, v124, v110
	v_mul_f32_e32 v125, v125, v111
	v_cvt_pk_bf16_f32 v126, v118, v119
	v_cvt_pk_bf16_f32 v127, v120, v121
	v_cvt_pk_bf16_f32 v128, v122, v123
	v_cvt_pk_bf16_f32 v129, v124, v125
	global_store_dwordx4 v131, v[126:129], s[30:31]
.Lp8_main:
	s_min_u32 s5, s20, 0x1ff
	s_mul_i32 s5, s5, 0xb000
	s_add_u32 s24, s10, s5
	s_addc_u32 s25, s11, 0
	s_sub_u32 s26, s24, 0x2c00
	s_subb_u32 s27, s25, 0
	s_sub_u32 s28, s24, 0x5800
	s_subb_u32 s29, s25, 0
	global_load_dwordx4 v[64:67], v130, s[24:25]
	global_load_dwordx4 v[76:79], v130, s[24:25] offset:256
	global_load_dwordx4 v[68:71], v130, s[26:27]
	global_load_dwordx4 v[80:83], v130, s[26:27] offset:256
	global_load_dwordx4 v[72:75], v130, s[28:29]
	global_load_dwordx4 v[84:87], v130, s[28:29] offset:256
	s_min_u32 s5, s21, 0x1ff
	s_mul_i32 s5, s5, 0xb000
	s_add_u32 s24, s10, s5
	s_addc_u32 s25, s11, 0
	s_sub_u32 s26, s24, 0x2c00
	s_subb_u32 s27, s25, 0
	s_sub_u32 s28, s24, 0x5800
	s_subb_u32 s29, s25, 0
	global_load_dwordx4 v[88:91], v130, s[24:25]
	global_load_dwordx4 v[100:103], v130, s[24:25] offset:256
	global_load_dwordx4 v[92:95], v130, s[26:27]
	global_load_dwordx4 v[104:107], v130, s[26:27] offset:256
	global_load_dwordx4 v[96:99], v130, s[28:29]
	global_load_dwordx4 v[108:111], v130, s[28:29] offset:256
	s_waitcnt vmcnt(6)
	s_cmpk_ge_u32 s20, 0x200
	s_cbranch_scc1 .Lp8_skip0
	s_and_b32 s5, s20, 63
	s_cmp_eq_u32 s5, 0
	s_cbranch_scc1 .Lp8_skip0
	s_mul_i32 s5, s20, 0x58000
	s_add_u32 s30, s12, s5
	s_addc_u32 s31, s13, 0
	v_lshlrev_b32_e32 v112, 16, v64
	v_and_b32_e32 v113, 0xffff0000, v64
	v_lshlrev_b32_e32 v114, 16, v68
	v_and_b32_e32 v115, 0xffff0000, v68
	v_lshlrev_b32_e32 v116, 16, v72
	v_and_b32_e32 v117, 0xffff0000, v72
	v_fma_f32 v64, v0, v116, v48
	v_fmac_f32_e32 v64, v16, v114
	v_fmac_f32_e32 v64, v32, v112
	v_fma_f32 v68, v1, v117, v49
	v_fmac_f32_e32 v68, v17, v115
	v_fmac_f32_e32 v68, v33, v113
	v_lshlrev_b32_e32 v112, 16, v65
	v_and_b32_e32 v113, 0xffff0000, v65
	v_lshlrev_b32_e32 v114, 16, v69
	v_and_b32_e32 v115, 0xffff0000, v69
	v_lshlrev_b32_e32 v116, 16, v73
	v_and_b32_e32 v117, 0xffff0000, v73
	v_fma_f32 v65, v2, v116, v50
	v_fmac_f32_e32 v65, v18, v114
	v_fmac_f32_e32 v65, v34, v112
	v_fma_f32 v69, v3, v117, v51
	v_fmac_f32_e32 v69, v19, v115
	v_fmac_f32_e32 v69, v35, v113
	v_lshlrev_b32_e32 v112, 16, v66
	v_and_b32_e32 v113, 0xffff0000, v66
	v_lshlrev_b32_e32 v114, 16, v70
	v_and_b32_e32 v115, 0xffff0000, v70
	v_lshlrev_b32_e32 v116, 16, v74
	v_and_b32_e32 v117, 0xffff0000, v74
	v_fma_f32 v66, v4, v116, v52
	v_fmac_f32_e32 v66, v20, v114
	v_fmac_f32_e32 v66, v36, v112
	v_fma_f32 v70, v5, v117, v53
	v_fmac_f32_e32 v70, v21, v115
	v_fmac_f32_e32 v70, v37, v113
	v_lshlrev_b32_e32 v112, 16, v67
	v_and_b32_e32 v113, 0xffff0000, v67
	v_lshlrev_b32_e32 v114, 16, v71
	v_and_b32_e32 v115, 0xffff0000, v71
	v_lshlrev_b32_e32 v116, 16, v75
	v_and_b32_e32 v117, 0xffff0000, v75
	v_fma_f32 v67, v6, v116, v54
	v_fmac_f32_e32 v67, v22, v114
	v_fmac_f32_e32 v67, v38, v112
	v_fma_f32 v71, v7, v117, v55
	v_fmac_f32_e32 v71, v23, v115
	v_fmac_f32_e32 v71, v39, v113
	v_lshlrev_b32_e32 v112, 16, v76
	v_and_b32_e32 v113, 0xffff0000, v76
	v_lshlrev_b32_e32 v114, 16, v80
	v_and_b32_e32 v115, 0xffff0000, v80
	v_lshlrev_b32_e32 v116, 16, v84
	v_and_b32_e32 v117, 0xffff0000, v84
	v_fma_f32 v76, v8, v116, v56
	v_fmac_f32_e32 v76, v24, v114
	v_fmac_f32_e32 v76, v40, v112
	v_fma_f32 v80, v9, v117, v57
	v_fmac_f32_e32 v80, v25, v115
	v_fmac_f32_e32 v80, v41, v113
	v_lshlrev_b32_e32 v112, 16, v77
	v_and_b32_e32 v113, 0xffff0000, v77
	v_lshlrev_b32_e32 v114, 16, v81
	v_and_b32_e32 v115, 0xffff0000, v81
	v_lshlrev_b32_e32 v116, 16, v85
	v_and_b32_e32 v117, 0xffff0000, v85
	v_fma_f32 v77, v10, v116, v58
	v_fmac_f32_e32 v77, v26, v114
	v_fmac_f32_e32 v77, v42, v112
	v_fma_f32 v81, v11, v117, v59
	v_fmac_f32_e32 v81, v27, v115
	v_fmac_f32_e32 v81, v43, v113
	v_lshlrev_b32_e32 v112, 16, v78
	v_and_b32_e32 v113, 0xffff0000, v78
	v_lshlrev_b32_e32 v114, 16, v82
	v_and_b32_e32 v115, 0xffff0000, v82
	v_lshlrev_b32_e32 v116, 16, v86
	v_and_b32_e32 v117, 0xffff0000, v86
	v_fma_f32 v78, v12, v116, v60
	v_fmac_f32_e32 v78, v28, v114
	v_fmac_f32_e32 v78, v44, v112
	v_fma_f32 v82, v13, v117, v61
	v_fmac_f32_e32 v82, v29, v115
	v_fmac_f32_e32 v82, v45, v113
	v_lshlrev_b32_e32 v112, 16, v79
	v_and_b32_e32 v113, 0xffff0000, v79
	v_lshlrev_b32_e32 v114, 16, v83
	v_and_b32_e32 v115, 0xffff0000, v83
	v_lshlrev_b32_e32 v116, 16, v87
	v_and_b32_e32 v117, 0xffff0000, v87
	v_fma_f32 v79, v14, v116, v62
	v_fmac_f32_e32 v79, v30, v114
	v_fmac_f32_e32 v79, v46, v112
	v_fma_f32 v83, v15, v117, v63
	v_fmac_f32_e32 v83, v31, v115
	v_fmac_f32_e32 v83, v47, v113
	v_mul_f32_e32 v118, 0xbfb8aa3b, v64
	v_mul_f32_e32 v119, 0xbfb8aa3b, v68
	v_mul_f32_e32 v120, 0xbfb8aa3b, v65
	v_mul_f32_e32 v121, 0xbfb8aa3b, v69
	v_mul_f32_e32 v122, 0xbfb8aa3b, v66
	v_mul_f32_e32 v123, 0xbfb8aa3b, v70
	v_mul_f32_e32 v124, 0xbfb8aa3b, v67
	v_mul_f32_e32 v125, 0xbfb8aa3b, v71
	v_exp_f32_e32 v118, v118
	v_exp_f32_e32 v119, v119
	v_exp_f32_e32 v120, v120
	v_exp_f32_e32 v121, v121
	v_exp_f32_e32 v122, v122
	v_exp_f32_e32 v123, v123
	v_exp_f32_e32 v124, v124
	v_exp_f32_e32 v125, v125
	v_add_f32_e32 v118, 1.0, v118
	v_add_f32_e32 v119, 1.0, v119
	v_add_f32_e32 v120, 1.0, v120
	v_add_f32_e32 v121, 1.0, v121
	v_add_f32_e32 v122, 1.0, v122
	v_add_f32_e32 v123, 1.0, v123
	v_add_f32_e32 v124, 1.0, v124
	v_add_f32_e32 v125, 1.0, v125
	v_rcp_f32_e32 v118, v118
	v_rcp_f32_e32 v119, v119
	v_rcp_f32_e32 v120, v120
	v_rcp_f32_e32 v121, v121
	v_rcp_f32_e32 v122, v122
	v_rcp_f32_e32 v123, v123
	v_rcp_f32_e32 v124, v124
	v_rcp_f32_e32 v125, v125
	v_mul_f32_e32 v118, v64, v118
	v_mul_f32_e32 v119, v68, v119
	v_mul_f32_e32 v120, v65, v120
	v_mul_f32_e32 v121, v69, v121
	v_mul_f32_e32 v122, v66, v122
	v_mul_f32_e32 v123, v70, v123
	v_mul_f32_e32 v124, v67, v124
	v_mul_f32_e32 v125, v71, v125
	v_mul_f32_e32 v118, v118, v76
	v_mul_f32_e32 v119, v119, v80
	v_mul_f32_e32 v120, v120, v77
	v_mul_f32_e32 v121, v121, v81
	v_mul_f32_e32 v122, v122, v78
	v_mul_f32_e32 v123, v123, v82
	v_mul_f32_e32 v124, v124, v79
	v_mul_f32_e32 v125, v125, v83
	v_cvt_pk_bf16_f32 v126, v118, v119
	v_cvt_pk_bf16_f32 v127, v120, v121
	v_cvt_pk_bf16_f32 v128, v122, v123
	v_cvt_pk_bf16_f32 v129, v124, v125
	global_store_dwordx4 v131, v[126:129], s[30:31]
.Lp8_skip0:
	s_nop 1
	s_min_u32 s5, s22, 0x1ff
	s_mul_i32 s5, s5, 0xb000
	s_add_u32 s24, s10, s5
	s_addc_u32 s25, s11, 0
	s_sub_u32 s26, s24, 0x2c00
	s_subb_u32 s27, s25, 0
	s_sub_u32 s28, s24, 0x5800
	s_subb_u32 s29, s25, 0
	global_load_dwordx4 v[64:67], v130, s[24:25]
	global_load_dwordx4 v[76:79], v130, s[24:25] offset:256
	global_load_dwordx4 v[68:71], v130, s[26:27]
	global_load_dwordx4 v[80:83], v130, s[26:27] offset:256
	global_load_dwordx4 v[72:75], v130, s[28:29]
	global_load_dwordx4 v[84:87], v130, s[28:29] offset:256
	s_waitcnt vmcnt(6)
	s_cmpk_ge_u32 s21, 0x200
	s_cbranch_scc1 .Lp8_skip1
	s_and_b32 s5, s21, 63
	s_cmp_eq_u32 s5, 0
	s_cbranch_scc1 .Lp8_skip1
	s_mul_i32 s5, s21, 0x58000
	s_add_u32 s30, s12, s5
	s_addc_u32 s31, s13, 0
	v_lshlrev_b32_e32 v112, 16, v88
	v_and_b32_e32 v113, 0xffff0000, v88
	v_lshlrev_b32_e32 v114, 16, v92
	v_and_b32_e32 v115, 0xffff0000, v92
	v_lshlrev_b32_e32 v116, 16, v96
	v_and_b32_e32 v117, 0xffff0000, v96
	v_fma_f32 v88, v0, v116, v48
	v_fmac_f32_e32 v88, v16, v114
	v_fmac_f32_e32 v88, v32, v112
	v_fma_f32 v92, v1, v117, v49
	v_fmac_f32_e32 v92, v17, v115
	v_fmac_f32_e32 v92, v33, v113
	v_lshlrev_b32_e32 v112, 16, v89
	v_and_b32_e32 v113, 0xffff0000, v89
	v_lshlrev_b32_e32 v114, 16, v93
	v_and_b32_e32 v115, 0xffff0000, v93
	v_lshlrev_b32_e32 v116, 16, v97
	v_and_b32_e32 v117, 0xffff0000, v97
	v_fma_f32 v89, v2, v116, v50
	v_fmac_f32_e32 v89, v18, v114
	v_fmac_f32_e32 v89, v34, v112
	v_fma_f32 v93, v3, v117, v51
	v_fmac_f32_e32 v93, v19, v115
	v_fmac_f32_e32 v93, v35, v113
	v_lshlrev_b32_e32 v112, 16, v90
	v_and_b32_e32 v113, 0xffff0000, v90
	v_lshlrev_b32_e32 v114, 16, v94
	v_and_b32_e32 v115, 0xffff0000, v94
	v_lshlrev_b32_e32 v116, 16, v98
	v_and_b32_e32 v117, 0xffff0000, v98
	v_fma_f32 v90, v4, v116, v52
	v_fmac_f32_e32 v90, v20, v114
	v_fmac_f32_e32 v90, v36, v112
	v_fma_f32 v94, v5, v117, v53
	v_fmac_f32_e32 v94, v21, v115
	v_fmac_f32_e32 v94, v37, v113
	v_lshlrev_b32_e32 v112, 16, v91
	v_and_b32_e32 v113, 0xffff0000, v91
	v_lshlrev_b32_e32 v114, 16, v95
	v_and_b32_e32 v115, 0xffff0000, v95
	v_lshlrev_b32_e32 v116, 16, v99
	v_and_b32_e32 v117, 0xffff0000, v99
	v_fma_f32 v91, v6, v116, v54
	v_fmac_f32_e32 v91, v22, v114
	v_fmac_f32_e32 v91, v38, v112
	v_fma_f32 v95, v7, v117, v55
	v_fmac_f32_e32 v95, v23, v115
	v_fmac_f32_e32 v95, v39, v113
	v_lshlrev_b32_e32 v112, 16, v100
	v_and_b32_e32 v113, 0xffff0000, v100
	v_lshlrev_b32_e32 v114, 16, v104
	v_and_b32_e32 v115, 0xffff0000, v104
	v_lshlrev_b32_e32 v116, 16, v108
	v_and_b32_e32 v117, 0xffff0000, v108
	v_fma_f32 v100, v8, v116, v56
	v_fmac_f32_e32 v100, v24, v114
	v_fmac_f32_e32 v100, v40, v112
	v_fma_f32 v104, v9, v117, v57
	v_fmac_f32_e32 v104, v25, v115
	v_fmac_f32_e32 v104, v41, v113
	v_lshlrev_b32_e32 v112, 16, v101
	v_and_b32_e32 v113, 0xffff0000, v101
	v_lshlrev_b32_e32 v114, 16, v105
	v_and_b32_e32 v115, 0xffff0000, v105
	v_lshlrev_b32_e32 v116, 16, v109
	v_and_b32_e32 v117, 0xffff0000, v109
	v_fma_f32 v101, v10, v116, v58
	v_fmac_f32_e32 v101, v26, v114
	v_fmac_f32_e32 v101, v42, v112
	v_fma_f32 v105, v11, v117, v59
	v_fmac_f32_e32 v105, v27, v115
	v_fmac_f32_e32 v105, v43, v113
	v_lshlrev_b32_e32 v112, 16, v102
	v_and_b32_e32 v113, 0xffff0000, v102
	v_lshlrev_b32_e32 v114, 16, v106
	v_and_b32_e32 v115, 0xffff0000, v106
	v_lshlrev_b32_e32 v116, 16, v110
	v_and_b32_e32 v117, 0xffff0000, v110
	v_fma_f32 v102, v12, v116, v60
	v_fmac_f32_e32 v102, v28, v114
	v_fmac_f32_e32 v102, v44, v112
	v_fma_f32 v106, v13, v117, v61
	v_fmac_f32_e32 v106, v29, v115
	v_fmac_f32_e32 v106, v45, v113
	v_lshlrev_b32_e32 v112, 16, v103
	v_and_b32_e32 v113, 0xffff0000, v103
	v_lshlrev_b32_e32 v114, 16, v107
	v_and_b32_e32 v115, 0xffff0000, v107
	v_lshlrev_b32_e32 v116, 16, v111
	v_and_b32_e32 v117, 0xffff0000, v111
	v_fma_f32 v103, v14, v116, v62
	v_fmac_f32_e32 v103, v30, v114
	v_fmac_f32_e32 v103, v46, v112
	v_fma_f32 v107, v15, v117, v63
	v_fmac_f32_e32 v107, v31, v115
	v_fmac_f32_e32 v107, v47, v113
	v_mul_f32_e32 v118, 0xbfb8aa3b, v88
	v_mul_f32_e32 v119, 0xbfb8aa3b, v92
	v_mul_f32_e32 v120, 0xbfb8aa3b, v89
	v_mul_f32_e32 v121, 0xbfb8aa3b, v93
	v_mul_f32_e32 v122, 0xbfb8aa3b, v90
	v_mul_f32_e32 v123, 0xbfb8aa3b, v94
	v_mul_f32_e32 v124, 0xbfb8aa3b, v91
	v_mul_f32_e32 v125, 0xbfb8aa3b, v95
	v_exp_f32_e32 v118, v118
	v_exp_f32_e32 v119, v119
	v_exp_f32_e32 v120, v120
	v_exp_f32_e32 v121, v121
	v_exp_f32_e32 v122, v122
	v_exp_f32_e32 v123, v123
	v_exp_f32_e32 v124, v124
	v_exp_f32_e32 v125, v125
	v_add_f32_e32 v118, 1.0, v118
	v_add_f32_e32 v119, 1.0, v119
	v_add_f32_e32 v120, 1.0, v120
	v_add_f32_e32 v121, 1.0, v121
	v_add_f32_e32 v122, 1.0, v122
	v_add_f32_e32 v123, 1.0, v123
	v_add_f32_e32 v124, 1.0, v124
	v_add_f32_e32 v125, 1.0, v125
	v_rcp_f32_e32 v118, v118
	v_rcp_f32_e32 v119, v119
	v_rcp_f32_e32 v120, v120
	v_rcp_f32_e32 v121, v121
	v_rcp_f32_e32 v122, v122
	v_rcp_f32_e32 v123, v123
	v_rcp_f32_e32 v124, v124
	v_rcp_f32_e32 v125, v125
	v_mul_f32_e32 v118, v88, v118
	v_mul_f32_e32 v119, v92, v119
	v_mul_f32_e32 v120, v89, v120
	v_mul_f32_e32 v121, v93, v121
	v_mul_f32_e32 v122, v90, v122
	v_mul_f32_e32 v123, v94, v123
	v_mul_f32_e32 v124, v91, v124
	v_mul_f32_e32 v125, v95, v125
	v_mul_f32_e32 v118, v118, v100
	v_mul_f32_e32 v119, v119, v104
	v_mul_f32_e32 v120, v120, v101
	v_mul_f32_e32 v121, v121, v105
	v_mul_f32_e32 v122, v122, v102
	v_mul_f32_e32 v123, v123, v106
	v_mul_f32_e32 v124, v124, v103
	v_mul_f32_e32 v125, v125, v107
	v_cvt_pk_bf16_f32 v126, v118, v119
	v_cvt_pk_bf16_f32 v127, v120, v121
	v_cvt_pk_bf16_f32 v128, v122, v123
	v_cvt_pk_bf16_f32 v129, v124, v125
	global_store_dwordx4 v131, v[126:129], s[30:31]
.Lp8_skip1:
	s_waitcnt vmcnt(0)
	s_cmpk_ge_u32 s22, 0x200
	s_cbranch_scc1 .Lp8_skip2
	s_and_b32 s5, s22, 63
	s_cmp_eq_u32 s5, 0
	s_cbranch_scc1 .Lp8_skip2
	s_mul_i32 s5, s22, 0x58000
	s_add_u32 s30, s12, s5
	s_addc_u32 s31, s13, 0
	v_lshlrev_b32_e32 v112, 16, v64
	v_and_b32_e32 v113, 0xffff0000, v64
	v_lshlrev_b32_e32 v114, 16, v68
	v_and_b32_e32 v115, 0xffff0000, v68
	v_lshlrev_b32_e32 v116, 16, v72
	v_and_b32_e32 v117, 0xffff0000, v72
	v_fma_f32 v64, v0, v116, v48
	v_fmac_f32_e32 v64, v16, v114
	v_fmac_f32_e32 v64, v32, v112
	v_fma_f32 v68, v1, v117, v49
	v_fmac_f32_e32 v68, v17, v115
	v_fmac_f32_e32 v68, v33, v113
	v_lshlrev_b32_e32 v112, 16, v65
	v_and_b32_e32 v113, 0xffff0000, v65
	v_lshlrev_b32_e32 v114, 16, v69
	v_and_b32_e32 v115, 0xffff0000, v69
	v_lshlrev_b32_e32 v116, 16, v73
	v_and_b32_e32 v117, 0xffff0000, v73
	v_fma_f32 v65, v2, v116, v50
	v_fmac_f32_e32 v65, v18, v114
	v_fmac_f32_e32 v65, v34, v112
	v_fma_f32 v69, v3, v117, v51
	v_fmac_f32_e32 v69, v19, v115
	v_fmac_f32_e32 v69, v35, v113
	v_lshlrev_b32_e32 v112, 16, v66
	v_and_b32_e32 v113, 0xffff0000, v66
	v_lshlrev_b32_e32 v114, 16, v70
	v_and_b32_e32 v115, 0xffff0000, v70
	v_lshlrev_b32_e32 v116, 16, v74
	v_and_b32_e32 v117, 0xffff0000, v74
	v_fma_f32 v66, v4, v116, v52
	v_fmac_f32_e32 v66, v20, v114
	v_fmac_f32_e32 v66, v36, v112
	v_fma_f32 v70, v5, v117, v53
	v_fmac_f32_e32 v70, v21, v115
	v_fmac_f32_e32 v70, v37, v113
	v_lshlrev_b32_e32 v112, 16, v67
	v_and_b32_e32 v113, 0xffff0000, v67
	v_lshlrev_b32_e32 v114, 16, v71
	v_and_b32_e32 v115, 0xffff0000, v71
	v_lshlrev_b32_e32 v116, 16, v75
	v_and_b32_e32 v117, 0xffff0000, v75
	v_fma_f32 v67, v6, v116, v54
	v_fmac_f32_e32 v67, v22, v114
	v_fmac_f32_e32 v67, v38, v112
	v_fma_f32 v71, v7, v117, v55
	v_fmac_f32_e32 v71, v23, v115
	v_fmac_f32_e32 v71, v39, v113
	v_lshlrev_b32_e32 v112, 16, v76
	v_and_b32_e32 v113, 0xffff0000, v76
	v_lshlrev_b32_e32 v114, 16, v80
	v_and_b32_e32 v115, 0xffff0000, v80
	v_lshlrev_b32_e32 v116, 16, v84
	v_and_b32_e32 v117, 0xffff0000, v84
	v_fma_f32 v76, v8, v116, v56
	v_fmac_f32_e32 v76, v24, v114
	v_fmac_f32_e32 v76, v40, v112
	v_fma_f32 v80, v9, v117, v57
	v_fmac_f32_e32 v80, v25, v115
	v_fmac_f32_e32 v80, v41, v113
	v_lshlrev_b32_e32 v112, 16, v77
	v_and_b32_e32 v113, 0xffff0000, v77
	v_lshlrev_b32_e32 v114, 16, v81
	v_and_b32_e32 v115, 0xffff0000, v81
	v_lshlrev_b32_e32 v116, 16, v85
	v_and_b32_e32 v117, 0xffff0000, v85
	v_fma_f32 v77, v10, v116, v58
	v_fmac_f32_e32 v77, v26, v114
	v_fmac_f32_e32 v77, v42, v112
	v_fma_f32 v81, v11, v117, v59
	v_fmac_f32_e32 v81, v27, v115
	v_fmac_f32_e32 v81, v43, v113
	v_lshlrev_b32_e32 v112, 16, v78
	v_and_b32_e32 v113, 0xffff0000, v78
	v_lshlrev_b32_e32 v114, 16, v82
	v_and_b32_e32 v115, 0xffff0000, v82
	v_lshlrev_b32_e32 v116, 16, v86
	v_and_b32_e32 v117, 0xffff0000, v86
	v_fma_f32 v78, v12, v116, v60
	v_fmac_f32_e32 v78, v28, v114
	v_fmac_f32_e32 v78, v44, v112
	v_fma_f32 v82, v13, v117, v61
	v_fmac_f32_e32 v82, v29, v115
	v_fmac_f32_e32 v82, v45, v113
	v_lshlrev_b32_e32 v112, 16, v79
	v_and_b32_e32 v113, 0xffff0000, v79
	v_lshlrev_b32_e32 v114, 16, v83
	v_and_b32_e32 v115, 0xffff0000, v83
	v_lshlrev_b32_e32 v116, 16, v87
	v_and_b32_e32 v117, 0xffff0000, v87
	v_fma_f32 v79, v14, v116, v62
	v_fmac_f32_e32 v79, v30, v114
	v_fmac_f32_e32 v79, v46, v112
	v_fma_f32 v83, v15, v117, v63
	v_fmac_f32_e32 v83, v31, v115
	v_fmac_f32_e32 v83, v47, v113
	v_mul_f32_e32 v118, 0xbfb8aa3b, v64
	v_mul_f32_e32 v119, 0xbfb8aa3b, v68
	v_mul_f32_e32 v120, 0xbfb8aa3b, v65
	v_mul_f32_e32 v121, 0xbfb8aa3b, v69
	v_mul_f32_e32 v122, 0xbfb8aa3b, v66
	v_mul_f32_e32 v123, 0xbfb8aa3b, v70
	v_mul_f32_e32 v124, 0xbfb8aa3b, v67
	v_mul_f32_e32 v125, 0xbfb8aa3b, v71
	v_exp_f32_e32 v118, v118
	v_exp_f32_e32 v119, v119
	v_exp_f32_e32 v120, v120
	v_exp_f32_e32 v121, v121
	v_exp_f32_e32 v122, v122
	v_exp_f32_e32 v123, v123
	v_exp_f32_e32 v124, v124
	v_exp_f32_e32 v125, v125
	v_add_f32_e32 v118, 1.0, v118
	v_add_f32_e32 v119, 1.0, v119
	v_add_f32_e32 v120, 1.0, v120
	v_add_f32_e32 v121, 1.0, v121
	v_add_f32_e32 v122, 1.0, v122
	v_add_f32_e32 v123, 1.0, v123
	v_add_f32_e32 v124, 1.0, v124
	v_add_f32_e32 v125, 1.0, v125
	v_rcp_f32_e32 v118, v118
	v_rcp_f32_e32 v119, v119
	v_rcp_f32_e32 v120, v120
	v_rcp_f32_e32 v121, v121
	v_rcp_f32_e32 v122, v122
	v_rcp_f32_e32 v123, v123
	v_rcp_f32_e32 v124, v124
	v_rcp_f32_e32 v125, v125
	v_mul_f32_e32 v118, v64, v118
	v_mul_f32_e32 v119, v68, v119
	v_mul_f32_e32 v120, v65, v120
	v_mul_f32_e32 v121, v69, v121
	v_mul_f32_e32 v122, v66, v122
	v_mul_f32_e32 v123, v70, v123
	v_mul_f32_e32 v124, v67, v124
	v_mul_f32_e32 v125, v71, v125
	v_mul_f32_e32 v118, v118, v76
	v_mul_f32_e32 v119, v119, v80
	v_mul_f32_e32 v120, v120, v77
	v_mul_f32_e32 v121, v121, v81
	v_mul_f32_e32 v122, v122, v78
	v_mul_f32_e32 v123, v123, v82
	v_mul_f32_e32 v124, v124, v79
	v_mul_f32_e32 v125, v125, v83
	v_cvt_pk_bf16_f32 v126, v118, v119
	v_cvt_pk_bf16_f32 v127, v120, v121
	v_cvt_pk_bf16_f32 v128, v122, v123
	v_cvt_pk_bf16_f32 v129, v124, v125
	global_store_dwordx4 v131, v[126:129], s[30:31]
.Lp8_skip2:
	s_add_u32 s40, s22, s3
	s_cmpk_lt_u32 s40, 0x200
	s_cbranch_scc1 .Lp8_pass
.Lp8_done:
.LBB0_1198:
	v_readlane_b32 s4, v240, 2
	v_readlane_b32 s5, v240, 3
	s_cmp_gt_i32 s5, 9
	s_cselect_b64 s[4:5], -1, 0
	s_and_b64 s[0:1], s[0:1], s[4:5]
	s_andn2_b64 vcc, exec, s[0:1]
	s_cbranch_vccnz .LBB0_1252
	s_waitcnt vmcnt(0)
	s_waitcnt vmcnt(0)
	s_barrier
	s_mov_b64 s[0:1], exec
	v_readlane_b32 s6, v240, 23
	v_readlane_b32 s7, v240, 24
	s_and_b64 s[6:7], s[0:1], s[6:7]
	s_mov_b64 exec, s[6:7]
	s_cbranch_execz .LBB0_1251
	s_add_i32 s3, 0, 0x20040
	v_mov_b32_e32 v0, s3
	s_waitcnt vmcnt(0) expcnt(0) lgkmcnt(0)
	ds_read_b32 v2, v0
	s_add_i32 s3, 0, 0x20044
	v_mov_b32_e32 v0, s3
	ds_read_b32 v0, v0
	s_waitcnt lgkmcnt(1)
	v_cmp_ne_u32_e32 vcc, 0, v2
	s_cbranch_vccnz .LBB0_1215
	s_add_u32 s6, s94, 0xe0200
	s_addc_u32 s7, s95, 0
	s_add_u32 s8, s94, 0xe0400
	s_addc_u32 s9, s95, 0
	s_add_u32 s10, s94, 0xe0500
	s_addc_u32 s11, s95, 0
	s_add_u32 s12, s94, 0xe0600
	s_addc_u32 s13, s95, 0
	s_add_u32 s14, s94, 0xe0700
	s_addc_u32 s15, s95, 0
	s_add_u32 s16, s94, 0xe0800
	s_addc_u32 s17, s95, 0
	s_add_u32 s18, s94, 0xe0900
	s_addc_u32 s19, s95, 0
	s_add_u32 s20, s94, 0xe0a00
	s_addc_u32 s21, s95, 0
	s_add_u32 s22, s94, 0xe0b00
	s_addc_u32 s23, s95, 0
	s_add_u32 s24, s94, 0xe0c00
	s_addc_u32 s25, s95, 0
	s_add_u32 s26, s94, 0xe0d00
	s_addc_u32 s27, s95, 0
	s_add_u32 s28, s94, 0xe0e00
	s_addc_u32 s29, s95, 0
	s_add_u32 s30, s94, 0xe0f00
	s_addc_u32 s31, s95, 0
	s_add_u32 s34, s94, 0xe1000
	s_addc_u32 s35, s95, 0
	s_add_u32 s36, s94, 0xe1100
	s_addc_u32 s37, s95, 0
	s_add_u32 s38, s94, 0xe1200
	v_readlane_b32 s3, v240, 1
	s_addc_u32 s39, s95, 0
	s_mul_i32 s3, s97, s3
	s_add_u32 s40, s94, 0xe1300
	s_mul_i32 s3, s3, s96
	s_addc_u32 s41, s95, 0
	s_mov_b32 s33, 1
	v_mov_b32_e32 v16, 0
	s_branch .LBB0_1203
